# residual-stream loads in the residual epilogues marked nt (read once)
# baseline (speedup 1.0000x reference)
.LBB0_532:
	v_and_b32_e32 v130, 64, v209
	s_lshl_b32 s6, s81, 8
	v_xor_b32_e32 v0, 16, v209
	v_add_u32_e32 v130, 64, v130
	s_add_i32 s6, s6, s47
	v_cmp_lt_i32_e32 vcc, v0, v130
	v_xor_b32_e32 v131, 32, v209
	s_lshl_b32 s0, s34, 5
	v_add_u32_e32 v194, s6, v145
	s_lshl_b32 s6, s84, 8
	v_cndmask_b32_e32 v0, v209, v0, vcc
	v_cmp_lt_i32_e32 vcc, v131, v130
	s_or_b32 s0, s6, s0
	v_ashrrev_i32_e32 v195, 31, v194
	v_cndmask_b32_e32 v130, v209, v131, vcc
	v_lshl_or_b32 v166, v144, 3, s0
	v_lshlrev_b32_e32 v172, 2, v130
	v_lshlrev_b64 v[130:131], 12, v[194:195]
	v_ashrrev_i32_e32 v167, 31, v166
	v_lshl_add_u64 v[130:131], s[16:17], 0, v[130:131]
	v_lshl_add_u64 v[138:139], v[166:167], 2, v[130:131]
	s_barrier
	v_lshlrev_b32_e32 v0, 2, v0
	v_mov_b32_e32 v251, v172
	v_cmp_eq_u32_e32 vcc, 0, v144
	v_lshlrev_b32_e32 v200, 12, v194
	v_lshl_add_u32 v200, v166, 2, v200
	s_lshl_b32 s6, s84, 2
	s_ashr_i32 s7, s6, 31
	s_lshl_b64 s[6:7], s[6:7], 2
	s_add_u32 s0, s22, s6
	s_addc_u32 s7, s23, s7
	s_lshl_b32 s6, s34, 2
	s_add_u32 s6, s0, s6
	s_addc_u32 s7, s7, 0
	v_readlane_b32 s28, v254, 39
	s_mov_b32 s98, s36
	s_mov_b32 s83, 0x800000
	v_readlane_b32 s29, v254, 40
	v_readlane_b32 s48, v254, 41
	s_mov_b64 s[34:35], s[50:51]
	v_readlane_b32 s49, v254, 42
	s_mov_b64 s[8:9], s[16:17]
	global_load_dwordx4 v[150:153], v200, s[8:9] nt
	global_load_dwordx4 v[146:149], v200, s[8:9] offset:16 nt
	global_load_dwordx4 v[154:157], v200, s[8:9] offset:512 nt
	global_load_dwordx4 v[158:161], v200, s[8:9] offset:528 nt
	s_add_u32 s8, s16, 0x10000
	s_addc_u32 s9, s17, 0
	global_load_dwordx4 v[134:137], v200, s[8:9] nt
	global_load_dwordx4 v[130:133], v200, s[8:9] offset:16 nt
	global_load_dwordx4 v[138:141], v200, s[8:9] offset:512 nt
	global_load_dwordx4 v[142:145], v200, s[8:9] offset:528 nt
	s_add_u32 s8, s16, 0x20000
	s_addc_u32 s9, s17, 0
	global_load_dwordx4 v[210:213], v200, s[8:9] nt
	global_load_dwordx4 v[214:217], v200, s[8:9] offset:16 nt
	global_load_dwordx4 v[218:221], v200, s[8:9] offset:512 nt
	global_load_dwordx4 v[222:225], v200, s[8:9] offset:528 nt
	s_add_u32 s8, s16, 0x30000
	s_addc_u32 s9, s17, 0
	global_load_dwordx4 v[226:229], v200, s[8:9] nt
	global_load_dwordx4 v[230:233], v200, s[8:9] offset:16 nt
	global_load_dwordx4 v[234:237], v200, s[8:9] offset:512 nt
	global_load_dwordx4 v[238:241], v200, s[8:9] offset:528 nt
	s_waitcnt vmcnt(12)
	v_pk_fma_f32 v[150:151], s[18:19], v[126:127], v[150:151]
	v_pk_fma_f32 v[152:153], s[24:25], v[128:129], v[152:153]
	v_pk_fma_f32 v[146:147], s[18:19], v[122:123], v[146:147]
	v_pk_fma_f32 v[148:149], s[24:25], v[124:125], v[148:149]
	v_pk_fma_f32 v[154:155], s[18:19], v[118:119], v[154:155]
	v_pk_fma_f32 v[156:157], s[24:25], v[120:121], v[156:157]
	v_pk_fma_f32 v[158:159], s[18:19], v[114:115], v[158:159]
	v_pk_fma_f32 v[160:161], s[24:25], v[116:117], v[160:161]
	v_mul_f32_e32 v202, v153, v153
	v_mul_f32_e32 v201, v151, v151
	v_fmac_f32_e32 v201, v150, v150
	v_fmac_f32_e32 v202, v152, v152
	v_add_f32_e32 v201, v201, v202
	v_mul_f32_e32 v206, v149, v149
	v_mul_f32_e32 v203, v147, v147
	v_fmac_f32_e32 v203, v146, v146
	v_fmac_f32_e32 v206, v148, v148
	v_add_f32_e32 v203, v203, v206
	v_add_f32_e32 v201, v201, v203
	v_mul_f32_e32 v206, v157, v157
	v_mul_f32_e32 v203, v155, v155
	v_fmac_f32_e32 v203, v154, v154
	v_fmac_f32_e32 v206, v156, v156
	v_add_f32_e32 v203, v203, v206
	v_mul_f32_e32 v206, v161, v161
	v_mul_f32_e32 v202, v159, v159
	v_fmac_f32_e32 v202, v158, v158
	v_fmac_f32_e32 v206, v160, v160
	v_add_f32_e32 v202, v202, v206
	v_add_f32_e32 v203, v203, v202
	v_add_f32_e32 v242, v201, v203
	s_add_u32 s8, s16, 0x80000
	s_addc_u32 s9, s17, 0
	global_load_dwordx4 v[114:117], v200, s[8:9] nt
	global_load_dwordx4 v[118:121], v200, s[8:9] offset:16 nt
	global_load_dwordx4 v[122:125], v200, s[8:9] offset:512 nt
	global_load_dwordx4 v[126:129], v200, s[8:9] offset:528 nt
	s_waitcnt vmcnt(12)
	v_pk_fma_f32 v[134:135], s[18:19], v[110:111], v[134:135]
	v_pk_fma_f32 v[136:137], s[24:25], v[112:113], v[136:137]
	v_pk_fma_f32 v[130:131], s[18:19], v[106:107], v[130:131]
	v_pk_fma_f32 v[132:133], s[24:25], v[108:109], v[132:133]
	v_pk_fma_f32 v[138:139], s[18:19], v[102:103], v[138:139]
	v_pk_fma_f32 v[140:141], s[24:25], v[104:105], v[140:141]
	v_pk_fma_f32 v[142:143], s[18:19], v[98:99], v[142:143]
	v_pk_fma_f32 v[144:145], s[24:25], v[100:101], v[144:145]
	v_mul_f32_e32 v202, v137, v137
	v_mul_f32_e32 v201, v135, v135
	v_fmac_f32_e32 v201, v134, v134
	v_fmac_f32_e32 v202, v136, v136
	v_add_f32_e32 v201, v201, v202
	v_mul_f32_e32 v206, v133, v133
	v_mul_f32_e32 v203, v131, v131
	v_fmac_f32_e32 v203, v130, v130
	v_fmac_f32_e32 v206, v132, v132
	v_add_f32_e32 v203, v203, v206
	v_add_f32_e32 v201, v201, v203
	v_mul_f32_e32 v206, v141, v141
	v_mul_f32_e32 v203, v139, v139
	v_fmac_f32_e32 v203, v138, v138
	v_fmac_f32_e32 v206, v140, v140
	v_add_f32_e32 v203, v203, v206
	v_mul_f32_e32 v206, v145, v145
	v_mul_f32_e32 v202, v143, v143
	v_fmac_f32_e32 v202, v142, v142
	v_fmac_f32_e32 v206, v144, v144
	v_add_f32_e32 v202, v202, v206
	v_add_f32_e32 v203, v203, v202
	v_add_f32_e32 v243, v201, v203
	s_add_u32 s8, s16, 0x90000
	s_addc_u32 s9, s17, 0
	global_load_dwordx4 v[98:101], v200, s[8:9] nt
	global_load_dwordx4 v[102:105], v200, s[8:9] offset:16 nt
	global_load_dwordx4 v[106:109], v200, s[8:9] offset:512 nt
	global_load_dwordx4 v[110:113], v200, s[8:9] offset:528 nt
	s_waitcnt vmcnt(12)
	v_pk_fma_f32 v[86:87], s[18:19], v[86:87], v[210:211]
	v_pk_fma_f32 v[88:89], s[24:25], v[88:89], v[212:213]
	v_pk_fma_f32 v[82:83], s[18:19], v[82:83], v[214:215]
	v_pk_fma_f32 v[84:85], s[24:25], v[84:85], v[216:217]
	v_pk_fma_f32 v[90:91], s[18:19], v[90:91], v[218:219]
	v_pk_fma_f32 v[92:93], s[24:25], v[92:93], v[220:221]
	v_pk_fma_f32 v[94:95], s[18:19], v[94:95], v[222:223]
	v_pk_fma_f32 v[96:97], s[24:25], v[96:97], v[224:225]
	v_mul_f32_e32 v202, v89, v89
	v_mul_f32_e32 v201, v87, v87
	v_fmac_f32_e32 v201, v86, v86
	v_fmac_f32_e32 v202, v88, v88
	v_add_f32_e32 v201, v201, v202
	v_mul_f32_e32 v206, v85, v85
	v_mul_f32_e32 v203, v83, v83
	v_fmac_f32_e32 v203, v82, v82
	v_fmac_f32_e32 v206, v84, v84
	v_add_f32_e32 v203, v203, v206
	v_add_f32_e32 v201, v201, v203
	v_mul_f32_e32 v206, v93, v93
	v_mul_f32_e32 v203, v91, v91
	v_fmac_f32_e32 v203, v90, v90
	v_fmac_f32_e32 v206, v92, v92
	v_add_f32_e32 v203, v203, v206
	v_mul_f32_e32 v206, v97, v97
	v_mul_f32_e32 v202, v95, v95
	v_fmac_f32_e32 v202, v94, v94
	v_fmac_f32_e32 v206, v96, v96
	v_add_f32_e32 v202, v202, v206
	v_add_f32_e32 v203, v203, v202
	v_add_f32_e32 v244, v201, v203
	s_add_u32 s8, s16, 0xa0000
	s_addc_u32 s9, s17, 0
	global_load_dwordx4 v[210:213], v200, s[8:9] nt
	global_load_dwordx4 v[214:217], v200, s[8:9] offset:16 nt
	global_load_dwordx4 v[218:221], v200, s[8:9] offset:512 nt
	global_load_dwordx4 v[222:225], v200, s[8:9] offset:528 nt
	s_waitcnt vmcnt(12)
	v_pk_fma_f32 v[70:71], s[18:19], v[70:71], v[226:227]
	v_pk_fma_f32 v[72:73], s[24:25], v[72:73], v[228:229]
	v_pk_fma_f32 v[66:67], s[18:19], v[66:67], v[230:231]
	v_pk_fma_f32 v[68:69], s[24:25], v[68:69], v[232:233]
	v_pk_fma_f32 v[74:75], s[18:19], v[74:75], v[234:235]
	v_pk_fma_f32 v[76:77], s[24:25], v[76:77], v[236:237]
	v_pk_fma_f32 v[78:79], s[18:19], v[78:79], v[238:239]
	v_pk_fma_f32 v[80:81], s[24:25], v[80:81], v[240:241]
	v_mul_f32_e32 v202, v73, v73
	v_mul_f32_e32 v201, v71, v71
	v_fmac_f32_e32 v201, v70, v70
	v_fmac_f32_e32 v202, v72, v72
	v_add_f32_e32 v201, v201, v202
	v_mul_f32_e32 v206, v69, v69
	v_mul_f32_e32 v203, v67, v67
	v_fmac_f32_e32 v203, v66, v66
	v_fmac_f32_e32 v206, v68, v68
	v_add_f32_e32 v203, v203, v206
	v_add_f32_e32 v201, v201, v203
	v_mul_f32_e32 v206, v77, v77
	v_mul_f32_e32 v203, v75, v75
	v_fmac_f32_e32 v203, v74, v74
	v_fmac_f32_e32 v206, v76, v76
	v_add_f32_e32 v203, v203, v206
	v_mul_f32_e32 v206, v81, v81
	v_mul_f32_e32 v202, v79, v79
	v_fmac_f32_e32 v202, v78, v78
	v_fmac_f32_e32 v206, v80, v80
	v_add_f32_e32 v202, v202, v206
	v_add_f32_e32 v203, v203, v202
	v_add_f32_e32 v245, v201, v203
	s_add_u32 s8, s16, 0xb0000
	s_addc_u32 s9, s17, 0
	global_load_dwordx4 v[226:229], v200, s[8:9] nt
	global_load_dwordx4 v[230:233], v200, s[8:9] offset:16 nt
	global_load_dwordx4 v[234:237], v200, s[8:9] offset:512 nt
	global_load_dwordx4 v[238:241], v200, s[8:9] offset:528 nt
	s_waitcnt vmcnt(12)
	v_pk_fma_f32 v[54:55], s[18:19], v[54:55], v[114:115]
	v_pk_fma_f32 v[56:57], s[24:25], v[56:57], v[116:117]
	v_pk_fma_f32 v[50:51], s[18:19], v[50:51], v[118:119]
	v_pk_fma_f32 v[52:53], s[24:25], v[52:53], v[120:121]
	v_pk_fma_f32 v[58:59], s[18:19], v[58:59], v[122:123]
	v_pk_fma_f32 v[60:61], s[24:25], v[60:61], v[124:125]
	v_pk_fma_f32 v[62:63], s[18:19], v[62:63], v[126:127]
	v_pk_fma_f32 v[64:65], s[24:25], v[64:65], v[128:129]
	v_mul_f32_e32 v202, v57, v57
	v_mul_f32_e32 v201, v55, v55
	v_fmac_f32_e32 v201, v54, v54
	v_fmac_f32_e32 v202, v56, v56
	v_add_f32_e32 v201, v201, v202
	v_mul_f32_e32 v206, v53, v53
	v_mul_f32_e32 v203, v51, v51
	v_fmac_f32_e32 v203, v50, v50
	v_fmac_f32_e32 v206, v52, v52
	v_add_f32_e32 v203, v203, v206
	v_add_f32_e32 v201, v201, v203
	v_mul_f32_e32 v206, v61, v61
	v_mul_f32_e32 v203, v59, v59
	v_fmac_f32_e32 v203, v58, v58
	v_fmac_f32_e32 v206, v60, v60
	v_add_f32_e32 v203, v203, v206
	v_mul_f32_e32 v206, v65, v65
	v_mul_f32_e32 v202, v63, v63
	v_fmac_f32_e32 v202, v62, v62
	v_fmac_f32_e32 v206, v64, v64
	v_add_f32_e32 v202, v202, v206
	v_add_f32_e32 v203, v203, v202
	v_add_f32_e32 v246, v201, v203
	s_waitcnt vmcnt(8)
	v_pk_fma_f32 v[38:39], s[18:19], v[38:39], v[98:99]
	v_pk_fma_f32 v[40:41], s[24:25], v[40:41], v[100:101]
	v_pk_fma_f32 v[34:35], s[18:19], v[34:35], v[102:103]
	v_pk_fma_f32 v[36:37], s[24:25], v[36:37], v[104:105]
	v_pk_fma_f32 v[42:43], s[18:19], v[42:43], v[106:107]
	v_pk_fma_f32 v[44:45], s[24:25], v[44:45], v[108:109]
	v_pk_fma_f32 v[46:47], s[18:19], v[46:47], v[110:111]
	v_pk_fma_f32 v[48:49], s[24:25], v[48:49], v[112:113]
	v_mul_f32_e32 v202, v41, v41
	v_mul_f32_e32 v201, v39, v39
	v_fmac_f32_e32 v201, v38, v38
	v_fmac_f32_e32 v202, v40, v40
	v_add_f32_e32 v201, v201, v202
	v_mul_f32_e32 v206, v37, v37
	v_mul_f32_e32 v203, v35, v35
	v_fmac_f32_e32 v203, v34, v34
	v_fmac_f32_e32 v206, v36, v36
	v_add_f32_e32 v203, v203, v206
	v_add_f32_e32 v201, v201, v203
	v_mul_f32_e32 v206, v45, v45
	v_mul_f32_e32 v203, v43, v43
	v_fmac_f32_e32 v203, v42, v42
	v_fmac_f32_e32 v206, v44, v44
	v_add_f32_e32 v203, v203, v206
	v_mul_f32_e32 v206, v49, v49
	v_mul_f32_e32 v202, v47, v47
	v_fmac_f32_e32 v202, v46, v46
	v_fmac_f32_e32 v206, v48, v48
	v_add_f32_e32 v202, v202, v206
	v_add_f32_e32 v203, v203, v202
	v_add_f32_e32 v247, v201, v203
	s_waitcnt vmcnt(4)
	v_pk_fma_f32 v[22:23], s[18:19], v[22:23], v[210:211]
	v_pk_fma_f32 v[24:25], s[24:25], v[24:25], v[212:213]
	v_pk_fma_f32 v[18:19], s[18:19], v[18:19], v[214:215]
	v_pk_fma_f32 v[20:21], s[24:25], v[20:21], v[216:217]
	v_pk_fma_f32 v[26:27], s[18:19], v[26:27], v[218:219]
	v_pk_fma_f32 v[28:29], s[24:25], v[28:29], v[220:221]
	v_pk_fma_f32 v[30:31], s[18:19], v[30:31], v[222:223]
	v_pk_fma_f32 v[32:33], s[24:25], v[32:33], v[224:225]
	v_mul_f32_e32 v202, v25, v25
	v_mul_f32_e32 v201, v23, v23
	v_fmac_f32_e32 v201, v22, v22
	v_fmac_f32_e32 v202, v24, v24
	v_add_f32_e32 v201, v201, v202
	v_mul_f32_e32 v206, v21, v21
	v_mul_f32_e32 v203, v19, v19
	v_fmac_f32_e32 v203, v18, v18
	v_fmac_f32_e32 v206, v20, v20
	v_add_f32_e32 v203, v203, v206
	v_add_f32_e32 v201, v201, v203
	v_mul_f32_e32 v206, v29, v29
	v_mul_f32_e32 v203, v27, v27
	v_fmac_f32_e32 v203, v26, v26
	v_fmac_f32_e32 v206, v28, v28
	v_add_f32_e32 v203, v203, v206
	v_mul_f32_e32 v206, v33, v33
	v_mul_f32_e32 v202, v31, v31
	v_fmac_f32_e32 v202, v30, v30
	v_fmac_f32_e32 v206, v32, v32
	v_add_f32_e32 v202, v202, v206
	v_add_f32_e32 v203, v203, v202
	v_add_f32_e32 v248, v201, v203
	s_waitcnt vmcnt(0)
	v_pk_fma_f32 v[6:7], s[18:19], v[6:7], v[226:227]
	v_pk_fma_f32 v[8:9], s[24:25], v[8:9], v[228:229]
	v_pk_fma_f32 v[2:3], s[18:19], v[2:3], v[230:231]
	v_pk_fma_f32 v[4:5], s[24:25], v[4:5], v[232:233]
	v_pk_fma_f32 v[10:11], s[18:19], v[10:11], v[234:235]
	v_pk_fma_f32 v[12:13], s[24:25], v[12:13], v[236:237]
	v_pk_fma_f32 v[14:15], s[18:19], v[14:15], v[238:239]
	v_pk_fma_f32 v[16:17], s[24:25], v[16:17], v[240:241]
	v_mul_f32_e32 v202, v9, v9
	v_mul_f32_e32 v201, v7, v7
	v_fmac_f32_e32 v201, v6, v6
	v_fmac_f32_e32 v202, v8, v8
	v_add_f32_e32 v201, v201, v202
	v_mul_f32_e32 v206, v5, v5
	v_mul_f32_e32 v203, v3, v3
	v_fmac_f32_e32 v203, v2, v2
	v_fmac_f32_e32 v206, v4, v4
	v_add_f32_e32 v203, v203, v206
	v_add_f32_e32 v201, v201, v203
	v_mul_f32_e32 v206, v13, v13
	v_mul_f32_e32 v203, v11, v11
	v_fmac_f32_e32 v203, v10, v10
	v_fmac_f32_e32 v206, v12, v12
	v_add_f32_e32 v203, v203, v206
	v_mul_f32_e32 v206, v17, v17
	v_mul_f32_e32 v202, v15, v15
	v_fmac_f32_e32 v202, v14, v14
	v_fmac_f32_e32 v206, v16, v16
	v_add_f32_e32 v202, v202, v206
	v_add_f32_e32 v203, v203, v202
	v_add_f32_e32 v249, v201, v203
	ds_bpermute_b32 v168, v0, v242
	ds_bpermute_b32 v169, v0, v243
	ds_bpermute_b32 v170, v0, v244
	ds_bpermute_b32 v171, v0, v245
	ds_bpermute_b32 v172, v0, v246
	ds_bpermute_b32 v173, v0, v247
	ds_bpermute_b32 v174, v0, v248
	ds_bpermute_b32 v175, v0, v249
	s_waitcnt lgkmcnt(0)
	v_add_f32_e32 v242, v242, v168
	v_add_f32_e32 v243, v243, v169
	v_add_f32_e32 v244, v244, v170
	v_add_f32_e32 v245, v245, v171
	v_add_f32_e32 v246, v246, v172
	v_add_f32_e32 v247, v247, v173
	v_add_f32_e32 v248, v248, v174
	v_add_f32_e32 v249, v249, v175
	ds_bpermute_b32 v168, v251, v242
	ds_bpermute_b32 v169, v251, v243
	ds_bpermute_b32 v170, v251, v244
	ds_bpermute_b32 v171, v251, v245
	ds_bpermute_b32 v172, v251, v246
	ds_bpermute_b32 v173, v251, v247
	ds_bpermute_b32 v174, v251, v248
	ds_bpermute_b32 v175, v251, v249
	v_lshlrev_b32_e32 v201, 6, v194
	v_add_u32_e32 v202, 0x2000, v201
	s_waitcnt lgkmcnt(0)
	v_add_f32_e32 v242, v242, v168
	v_add_f32_e32 v243, v243, v169
	v_add_f32_e32 v244, v244, v170
	v_add_f32_e32 v245, v245, v171
	v_add_f32_e32 v246, v246, v172
	v_add_f32_e32 v247, v247, v173
	v_add_f32_e32 v248, v248, v174
	v_add_f32_e32 v249, v249, v175
	s_and_saveexec_b64 s[8:9], vcc
	global_store_dword v201, v242, s[6:7]
	global_store_dword v201, v243, s[6:7] offset:1024
	global_store_dword v201, v244, s[6:7] offset:2048
	global_store_dword v201, v245, s[6:7] offset:3072
	global_store_dword v202, v246, s[6:7]
	global_store_dword v202, v247, s[6:7] offset:1024
	global_store_dword v202, v248, s[6:7] offset:2048
	global_store_dword v202, v249, s[6:7] offset:3072
	s_or_b64 exec, exec, s[8:9]
	s_getreg_b32 s0, hwreg(HW_REG_XCC_ID, 0, 4)
	s_waitcnt vmcnt(0)
	s_waitcnt lgkmcnt(0)
	s_barrier
	s_mov_b64 s[6:7], exec
	v_readlane_b32 s8, v252, 4
	v_readlane_b32 s9, v252, 5
	s_and_b64 s[8:9], s[6:7], s[8:9]
	s_xor_b64 s[6:7], s[8:9], s[6:7]
	s_mov_b64 exec, s[8:9]
	s_cbranch_execz .LBB0_601
	v_readlane_b32 s8, v253, 9
	s_waitcnt vmcnt(0) expcnt(0) lgkmcnt(0)
	s_and_b32 s0, s0, 15
	v_mov_b32_e32 v0, s8
	ds_read_b32 v99, v0
	v_readlane_b32 s8, v253, 10
	s_waitcnt lgkmcnt(0)
	v_cmp_ne_u32_e32 vcc, 0, v99
	v_mov_b32_e32 v0, s8
	ds_read_b32 v98, v0
	s_cbranch_vccnz .LBB0_564
	s_mov_b32 s14, 1
	s_branch .LBB0_552

.LBB0_663:
	v_lshl_add_u32 v144, s15, 8, v146
	v_lshl_or_b32 v142, s14, 8, v148
	v_ashrrev_i32_e32 v145, 31, v144
	v_ashrrev_i32_e32 v143, 31, v142
	v_lshlrev_b64 v[140:141], 10, v[144:145]
	v_lshl_add_u64 v[140:141], v[140:141], 0, v[142:143]
	v_lshlrev_b64 v[140:141], 2, v[140:141]
	v_readlane_b32 s56, v253, 56
	v_readlane_b32 s70, v254, 6
	v_readlane_b32 s71, v254, 7
	s_mov_b64 s[54:55], s[70:71]
	s_mov_b64 s[28:29], -1
	s_and_b64 vcc, exec, s[6:7]
	v_readlane_b32 s57, v253, 57
	v_readlane_b32 s58, v253, 58
	v_readlane_b32 s59, v253, 59
	v_readlane_b32 s60, v253, 60
	v_readlane_b32 s61, v253, 61
	v_readlane_b32 s62, v253, 62
	v_readlane_b32 s63, v253, 63
	v_readlane_b32 s64, v254, 0
	v_readlane_b32 s65, v254, 1
	v_readlane_b32 s66, v254, 2
	v_readlane_b32 s67, v254, 3
	v_readlane_b32 s68, v254, 4
	v_readlane_b32 s69, v254, 5
	s_mov_b64 s[14:15], s[16:17]
	global_load_dwordx4 v[150:153], v140, s[14:15] nt
	global_load_dwordx4 v[154:157], v140, s[14:15] offset:16 nt
	global_load_dwordx4 v[158:161], v140, s[14:15] offset:512 nt
	global_load_dwordx4 v[166:169], v140, s[14:15] offset:528 nt
	s_add_u32 s14, s16, 0x10000
	s_addc_u32 s15, s17, 0
	global_load_dwordx4 v[170:173], v140, s[14:15] nt
	global_load_dwordx4 v[174:177], v140, s[14:15] offset:16 nt
	global_load_dwordx4 v[178:181], v140, s[14:15] offset:512 nt
	global_load_dwordx4 v[182:185], v140, s[14:15] offset:528 nt
	s_add_u32 s14, s16, 0x20000
	s_addc_u32 s15, s17, 0
	global_load_dwordx4 v[186:189], v140, s[14:15] nt
	global_load_dwordx4 v[190:193], v140, s[14:15] offset:16 nt
	global_load_dwordx4 v[194:197], v140, s[14:15] offset:512 nt
	global_load_dwordx4 v[198:201], v140, s[14:15] offset:528 nt
	s_add_u32 s14, s16, 0x30000
	s_addc_u32 s15, s17, 0
	global_load_dwordx4 v[210:213], v140, s[14:15] nt
	global_load_dwordx4 v[214:217], v140, s[14:15] offset:16 nt
	global_load_dwordx4 v[218:221], v140, s[14:15] offset:512 nt
	global_load_dwordx4 v[142:145], v140, s[14:15] offset:528 nt
	s_waitcnt vmcnt(12)
	v_pk_fma_f32 v[126:127], s[18:19], v[126:127], v[150:151]
	v_pk_fma_f32 v[128:129], s[22:23], v[128:129], v[152:153]
	v_pk_fma_f32 v[122:123], s[18:19], v[122:123], v[154:155]
	v_pk_fma_f32 v[124:125], s[22:23], v[124:125], v[156:157]
	v_pk_fma_f32 v[118:119], s[18:19], v[118:119], v[158:159]
	v_pk_fma_f32 v[120:121], s[22:23], v[120:121], v[160:161]
	v_pk_fma_f32 v[114:115], s[18:19], v[114:115], v[166:167]
	v_pk_fma_f32 v[116:117], s[22:23], v[116:117], v[168:169]
	s_add_u32 s14, s16, 0x80000
	s_addc_u32 s15, s17, 0
	global_load_dwordx4 v[150:153], v140, s[14:15] nt
	global_load_dwordx4 v[154:157], v140, s[14:15] offset:16 nt
	global_load_dwordx4 v[158:161], v140, s[14:15] offset:512 nt
	global_load_dwordx4 v[166:169], v140, s[14:15] offset:528 nt
	s_waitcnt vmcnt(12)
	v_pk_fma_f32 v[110:111], s[18:19], v[110:111], v[170:171]
	v_pk_fma_f32 v[112:113], s[22:23], v[112:113], v[172:173]
	v_pk_fma_f32 v[106:107], s[18:19], v[106:107], v[174:175]
	v_pk_fma_f32 v[108:109], s[22:23], v[108:109], v[176:177]
	v_pk_fma_f32 v[102:103], s[18:19], v[102:103], v[178:179]
	v_pk_fma_f32 v[104:105], s[22:23], v[104:105], v[180:181]
	v_pk_fma_f32 v[98:99], s[18:19], v[98:99], v[182:183]
	v_pk_fma_f32 v[100:101], s[22:23], v[100:101], v[184:185]
	s_add_u32 s14, s16, 0x90000
	s_addc_u32 s15, s17, 0
	global_load_dwordx4 v[170:173], v140, s[14:15] nt
	global_load_dwordx4 v[174:177], v140, s[14:15] offset:16 nt
	global_load_dwordx4 v[178:181], v140, s[14:15] offset:512 nt
	global_load_dwordx4 v[182:185], v140, s[14:15] offset:528 nt
	s_waitcnt vmcnt(12)
	v_pk_fma_f32 v[94:95], s[18:19], v[94:95], v[186:187]
	v_pk_fma_f32 v[96:97], s[22:23], v[96:97], v[188:189]
	v_pk_fma_f32 v[90:91], s[18:19], v[90:91], v[190:191]
	v_pk_fma_f32 v[92:93], s[22:23], v[92:93], v[192:193]
	v_pk_fma_f32 v[86:87], s[18:19], v[86:87], v[194:195]
	v_pk_fma_f32 v[88:89], s[22:23], v[88:89], v[196:197]
	v_pk_fma_f32 v[82:83], s[18:19], v[82:83], v[198:199]
	v_pk_fma_f32 v[84:85], s[22:23], v[84:85], v[200:201]
	s_add_u32 s14, s16, 0xa0000
	s_addc_u32 s15, s17, 0
	global_load_dwordx4 v[186:189], v140, s[14:15] nt
	global_load_dwordx4 v[190:193], v140, s[14:15] offset:16 nt
	global_load_dwordx4 v[194:197], v140, s[14:15] offset:512 nt
	global_load_dwordx4 v[198:201], v140, s[14:15] offset:528 nt
	s_waitcnt vmcnt(12)
	v_pk_fma_f32 v[78:79], s[18:19], v[78:79], v[210:211]
	v_pk_fma_f32 v[80:81], s[22:23], v[80:81], v[212:213]
	v_pk_fma_f32 v[74:75], s[18:19], v[74:75], v[214:215]
	v_pk_fma_f32 v[76:77], s[22:23], v[76:77], v[216:217]
	v_pk_fma_f32 v[70:71], s[18:19], v[70:71], v[218:219]
	v_pk_fma_f32 v[72:73], s[22:23], v[72:73], v[220:221]
	v_pk_fma_f32 v[66:67], s[18:19], v[66:67], v[142:143]
	v_pk_fma_f32 v[68:69], s[22:23], v[68:69], v[144:145]
	s_add_u32 s14, s16, 0xb0000
	s_addc_u32 s15, s17, 0
	global_load_dwordx4 v[210:213], v140, s[14:15] nt
	global_load_dwordx4 v[214:217], v140, s[14:15] offset:16 nt
	global_load_dwordx4 v[218:221], v140, s[14:15] offset:512 nt
	global_load_dwordx4 v[142:145], v140, s[14:15] offset:528 nt
	s_waitcnt vmcnt(12)
	v_pk_fma_f32 v[62:63], s[18:19], v[62:63], v[150:151]
	v_pk_fma_f32 v[64:65], s[22:23], v[64:65], v[152:153]
	v_pk_fma_f32 v[58:59], s[18:19], v[58:59], v[154:155]
	v_pk_fma_f32 v[60:61], s[22:23], v[60:61], v[156:157]
	v_pk_fma_f32 v[54:55], s[18:19], v[54:55], v[158:159]
	v_pk_fma_f32 v[56:57], s[22:23], v[56:57], v[160:161]
	v_pk_fma_f32 v[50:51], s[18:19], v[50:51], v[166:167]
	v_pk_fma_f32 v[52:53], s[22:23], v[52:53], v[168:169]
	s_waitcnt vmcnt(8)
	v_pk_fma_f32 v[46:47], s[18:19], v[46:47], v[170:171]
	v_pk_fma_f32 v[48:49], s[22:23], v[48:49], v[172:173]
	v_pk_fma_f32 v[42:43], s[18:19], v[42:43], v[174:175]
	v_pk_fma_f32 v[44:45], s[22:23], v[44:45], v[176:177]
	v_pk_fma_f32 v[38:39], s[18:19], v[38:39], v[178:179]
	v_pk_fma_f32 v[40:41], s[22:23], v[40:41], v[180:181]
	v_pk_fma_f32 v[34:35], s[18:19], v[34:35], v[182:183]
	v_pk_fma_f32 v[36:37], s[22:23], v[36:37], v[184:185]
	s_waitcnt vmcnt(4)
	v_pk_fma_f32 v[30:31], s[18:19], v[30:31], v[186:187]
	v_pk_fma_f32 v[32:33], s[22:23], v[32:33], v[188:189]
	v_pk_fma_f32 v[26:27], s[18:19], v[26:27], v[190:191]
	v_pk_fma_f32 v[28:29], s[22:23], v[28:29], v[192:193]
	v_pk_fma_f32 v[22:23], s[18:19], v[22:23], v[194:195]
	v_pk_fma_f32 v[24:25], s[22:23], v[24:25], v[196:197]
	v_pk_fma_f32 v[18:19], s[18:19], v[18:19], v[198:199]
	v_pk_fma_f32 v[20:21], s[22:23], v[20:21], v[200:201]
	s_waitcnt vmcnt(0)
	v_pk_fma_f32 v[14:15], s[18:19], v[14:15], v[210:211]
	v_pk_fma_f32 v[16:17], s[22:23], v[16:17], v[212:213]
	v_pk_fma_f32 v[10:11], s[18:19], v[10:11], v[214:215]
	v_pk_fma_f32 v[12:13], s[22:23], v[12:13], v[216:217]
	v_pk_fma_f32 v[6:7], s[18:19], v[6:7], v[218:219]
	v_pk_fma_f32 v[8:9], s[22:23], v[8:9], v[220:221]
	v_pk_fma_f32 v[2:3], s[18:19], v[2:3], v[142:143]
	v_pk_fma_f32 v[4:5], s[22:23], v[4:5], v[144:145]
	v_mov_b32_e32 v142, v140
	global_store_dwordx4 v142, v[126:129], s[54:55] nt
	global_store_dwordx4 v142, v[122:125], s[54:55] offset:16 nt
	global_store_dwordx4 v142, v[118:121], s[54:55] offset:512 nt
	global_store_dwordx4 v142, v[114:117], s[54:55] offset:528 nt
	v_add_u32_e32 v142, 0x10000, v140
	global_store_dwordx4 v142, v[110:113], s[54:55] nt
	global_store_dwordx4 v142, v[106:109], s[54:55] offset:16 nt
	global_store_dwordx4 v142, v[102:105], s[54:55] offset:512 nt
	global_store_dwordx4 v142, v[98:101], s[54:55] offset:528 nt
	v_add_u32_e32 v142, 0x20000, v140
	global_store_dwordx4 v142, v[94:97], s[54:55] nt
	global_store_dwordx4 v142, v[90:93], s[54:55] offset:16 nt
	global_store_dwordx4 v142, v[86:89], s[54:55] offset:512 nt
	global_store_dwordx4 v142, v[82:85], s[54:55] offset:528 nt
	v_add_u32_e32 v142, 0x30000, v140
	global_store_dwordx4 v142, v[78:81], s[54:55] nt
	global_store_dwordx4 v142, v[74:77], s[54:55] offset:16 nt
	global_store_dwordx4 v142, v[70:73], s[54:55] offset:512 nt
	global_store_dwordx4 v142, v[66:69], s[54:55] offset:528 nt
	v_add_u32_e32 v142, 0x80000, v140
	global_store_dwordx4 v142, v[62:65], s[54:55] nt
	global_store_dwordx4 v142, v[58:61], s[54:55] offset:16 nt
	global_store_dwordx4 v142, v[54:57], s[54:55] offset:512 nt
	global_store_dwordx4 v142, v[50:53], s[54:55] offset:528 nt
	v_add_u32_e32 v142, 0x90000, v140
	global_store_dwordx4 v142, v[46:49], s[54:55] nt
	global_store_dwordx4 v142, v[42:45], s[54:55] offset:16 nt
	global_store_dwordx4 v142, v[38:41], s[54:55] offset:512 nt
	global_store_dwordx4 v142, v[34:37], s[54:55] offset:528 nt
	v_add_u32_e32 v142, 0xa0000, v140
	global_store_dwordx4 v142, v[30:33], s[54:55] nt
	global_store_dwordx4 v142, v[26:29], s[54:55] offset:16 nt
	global_store_dwordx4 v142, v[22:25], s[54:55] offset:512 nt
	global_store_dwordx4 v142, v[18:21], s[54:55] offset:528 nt
	v_add_u32_e32 v142, 0xb0000, v140
	global_store_dwordx4 v142, v[14:17], s[54:55] nt
	global_store_dwordx4 v142, v[10:13], s[54:55] offset:16 nt
	global_store_dwordx4 v142, v[6:9], s[54:55] offset:512 nt
	global_store_dwordx4 v142, v[2:5], s[54:55] offset:528 nt
	s_mov_b64 s[14:15], 0xb0000
	s_cbranch_vccnz .LBB0_648
	s_andn2_b64 vcc, exec, s[10:11]
	s_cbranch_vccnz .LBB0_647
	s_barrier
	s_branch .LBB0_647
